# attention main loop: next key tile prefetched one step ahead into its own registers; lane^32 exchanges by v_permlane32_swap instead of ds_bpermute round trips
# baseline (speedup 1.0000x reference)
; __device__ __forceinline__ void attn_phase(const bf16_t* Q, const bf16_t* KF, const bf16_t* V, bf16_t* VT, bf16_t* O, LAS unsigned char* lds, unsigned* ctr) {
;     ...
;                 f32x16 z = {0.f, 0.f, 0.f, 0.f, 0.f, 0.f, 0.f, 0.f, 0.f, 0.f, 0.f, 0.f, 0.f, 0.f, 0.f, 0.f};
; #pragma unroll
;                 for (int kd = 0; kd < 4; ++kd) z = __builtin_amdgcn_mfma_f32_32x32x16_bf16(kfn[kd], qf[kd], z, 0, 0, 0);
;                 { const int ktn = kt > 0 ? kt - 1 : kt;
; #pragma unroll
;                   for (int kd = 0; kd < 4; ++kd) kfn[kd] = *(const bf16x8*)(kfw + (size_t)((ktn * 4 + kd) * 64 + lane) * 8); }
;                 bf16x8 vf[2][2];
; #pragma unroll
;                 for (int db = 0; db < 2; ++db)
; #pragma unroll
;                     for (int ks = 0; ks < 2; ++ks) vf[db][ks] = *(const bf16x8*)(vtb + (size_t)((((kt * 2 + db) * 2 + ks) * 64) + lane) * 8);
;                 float be[16], om[16];
; #pragma unroll
;                 for (int r = 0; r < 16; ++r) { const float e = __builtin_amdgcn_exp2f(-fmaxf(z[r], -80.0f)); be[r] = __builtin_amdgcn_rcpf(1.0f + e); om[r] = e * be[r]; }
;                 if (kt == qb) {
; #pragma unroll
;                     for (int r = 0; r < 16; ++r) { const int sl = 8 * (r >> 2) + 4 * hf + (r & 3); const bool valid = sl < c32; be[r] = valid ? be[r] : 0.f; om[r] = valid ? om[r] : 1.0f; } }
;                 float bp[4], pbp[4];
; #pragma unroll
;                 for (int q = 0; q < 4; ++q) { bp[q] = (om[4 * q] * om[4 * q + 1]) * (om[4 * q + 2] * om[4 * q + 3]); pbp[q] = __shfl_xor(bp[q], 32); }
;                 float after = Pc; float att[16];
; #pragma unroll
;                 for (int q = 3; q >= 0; --q) {
;                     const float off = hf == 0 ? after * pbp[q] : after;
;                     const float e3 = off, e2 = e3 * om[4 * q + 3], e1 = e2 * om[4 * q + 2], e0 = e1 * om[4 * q + 1];
;                     att[4 * q + 3] = be[4 * q + 3] * e3; att[4 * q + 2] = be[4 * q + 2] * e2; att[4 * q + 1] = be[4 * q + 1] * e1; att[4 * q] = be[4 * q] * e0;
;                     after *= bp[q] * pbp[q];
;                 }
;                 Pc = after;
; #pragma unroll
;                 for (int ks = 0; ks < 2; ++ks) {
.LBB0_1749:
	s_or_b64 exec, exec, s[86:87]
	v_readfirstlane_b32 s79, v0
	s_cmp_gt_u32 s79, 63
	s_mov_b64 s[86:87], -1
	s_cbranch_scc1 .LBB0_1744
	s_sub_i32 s9, 63, s79
	s_lshl_b32 s63, s9, 12
	v_lshl_or_b32 v28, v85, 1, s63
	global_load_dwordx4 v[0:3], v28, s[82:83]
	global_load_dwordx4 v[48:51], v28, s[84:85]
	global_load_dwordx4 v[16:19], v28, s[82:83] offset:1024
	global_load_dwordx4 v[52:55], v28, s[84:85] offset:1024
	global_load_dwordx4 v[20:23], v28, s[82:83] offset:2048
	global_load_dwordx4 v[56:59], v28, s[84:85] offset:2048
	global_load_dwordx4 v[24:27], v28, s[82:83] offset:3072
	global_load_dwordx4 v[60:63], v28, s[84:85] offset:3072
	v_or_b32_e32 v28, s63, v86
	s_waitcnt vmcnt(6)
	v_mfma_f32_32x32x16_bf16 v[0:15], v[0:3], v[48:51], 0
	s_waitcnt vmcnt(4)
	v_mfma_f32_32x32x16_bf16 v[0:15], v[16:19], v[52:55], v[0:15]
	v_and_b32_e32 v17, 64, v102
	v_xor_b32_e32 v16, 32, v102
	v_add_u32_e32 v17, 64, v17
	v_cmp_lt_i32_e32 vcc, v16, v17
	s_nop 1
	v_cndmask_b32_e32 v16, v102, v16, vcc
	s_waitcnt vmcnt(2)
	v_mfma_f32_32x32x16_bf16 v[0:15], v[20:23], v[56:59], v[0:15]
	v_lshlrev_b32_e32 v104, 2, v16
	global_load_dwordx4 v[20:23], v28, s[80:81]
	global_load_dwordx4 v[32:35], v28, s[80:81] offset:1024
	global_load_dwordx4 v[16:19], v28, s[80:81] offset:2048
	global_load_dwordx4 v[36:39], v28, s[80:81] offset:3072
	s_waitcnt vmcnt(4)
	v_mfma_f32_32x32x16_bf16 v[0:15], v[24:27], v[60:63], v[0:15]
	s_nop 11
	v_min_f32_e64 v1, -v1, s98
	v_min_f32_e64 v4, -v4, s98
	v_min_f32_e64 v5, -v5, s98
	v_min_f32_e64 v6, -v6, s98
	v_min_f32_e64 v7, -v7, s98
	v_min_f32_e64 v0, -v0, s98
	v_min_f32_e64 v2, -v2, s98
	v_min_f32_e64 v3, -v3, s98
	v_exp_f32_e32 v25, v1
	v_exp_f32_e32 v28, v4
	v_exp_f32_e32 v29, v5
	v_exp_f32_e32 v30, v6
	v_exp_f32_e32 v31, v7
	v_exp_f32_e32 v24, v0
	v_exp_f32_e32 v26, v2
	v_exp_f32_e32 v27, v3
	v_min_f32_e64 v9, -v9, s98
	v_min_f32_e64 v12, -v12, s98
	v_min_f32_e64 v13, -v13, s98
	v_min_f32_e64 v14, -v14, s98
	v_min_f32_e64 v15, -v15, s98
	v_min_f32_e64 v8, -v8, s98
	v_min_f32_e64 v10, -v10, s98
	v_min_f32_e64 v11, -v11, s98
	v_exp_f32_e32 v3, v9
	v_exp_f32_e32 v0, v12
	v_exp_f32_e32 v2, v13
	v_exp_f32_e32 v4, v14
	v_exp_f32_e32 v6, v15
	v_add_f32_e32 v9, 1.0, v25
	v_add_f32_e32 v12, 1.0, v28
	v_add_f32_e32 v13, 1.0, v29
	v_add_f32_e32 v14, 1.0, v30
	v_add_f32_e32 v15, 1.0, v31
	v_exp_f32_e32 v1, v8
	v_exp_f32_e32 v5, v10
	v_exp_f32_e32 v7, v11
	v_add_f32_e32 v8, 1.0, v24
	v_add_f32_e32 v10, 1.0, v26
	v_add_f32_e32 v11, 1.0, v27
	v_rcp_f32_e32 v64, v9
	v_rcp_f32_e32 v12, v12
	v_rcp_f32_e32 v74, v13
	v_rcp_f32_e32 v14, v14
	v_rcp_f32_e32 v75, v15
	v_rcp_f32_e32 v47, v8
	v_rcp_f32_e32 v72, v10
	v_rcp_f32_e32 v73, v11
	v_mul_f32_e32 v25, v25, v64
	v_mul_f32_e32 v28, v28, v12
	v_mul_f32_e32 v29, v29, v74
	v_mul_f32_e32 v30, v30, v14
	v_mul_f32_e32 v31, v31, v75
	v_mul_f32_e32 v24, v24, v47
	v_mul_f32_e32 v26, v26, v72
	v_mul_f32_e32 v27, v27, v73
	v_cndmask_b32_e64 v80, 0, v14, s[28:29]
	v_cndmask_b32_e64 v81, 1.0, v25, s[18:19]
	v_cndmask_b32_e64 v14, 1.0, v28, s[24:25]
	v_cndmask_b32_e64 v25, 1.0, v29, s[26:27]
	v_cndmask_b32_e64 v29, 1.0, v30, s[28:29]
	v_cndmask_b32_e64 v105, 1.0, v31, s[30:31]
	v_cndmask_b32_e64 v79, 0, v12, s[24:25]
	v_cndmask_b32_e64 v12, 1.0, v24, s[16:17]
	v_cndmask_b32_e64 v82, 1.0, v26, s[20:21]
	v_cndmask_b32_e64 v83, 1.0, v27, s[22:23]
	v_mul_f32_e32 v14, v14, v25
	v_mul_f32_e32 v26, v29, v105
	v_add_f32_e32 v40, 1.0, v1
	v_add_f32_e32 v41, 1.0, v3
	v_add_f32_e32 v42, 1.0, v5
	v_add_f32_e32 v43, 1.0, v7
	v_add_f32_e32 v44, 1.0, v0
	v_add_f32_e32 v45, 1.0, v2
	v_add_f32_e32 v46, 1.0, v4
	v_mul_f32_e32 v12, v12, v81
	v_mul_f32_e32 v24, v82, v83
	v_mul_f32_e32 v26, v14, v26
	v_add_f32_e32 v14, 1.0, v6
	v_rcp_f32_e32 v9, v40
	v_rcp_f32_e32 v11, v41
	v_rcp_f32_e32 v13, v42
	v_rcp_f32_e32 v15, v43
	v_rcp_f32_e32 v8, v44
	v_rcp_f32_e32 v10, v45
	v_mul_f32_e32 v24, v12, v24
	v_rcp_f32_e32 v12, v46
	v_rcp_f32_e32 v14, v14
	v_pk_mul_f32 v[0:1], v[0:1], v[8:9]
	v_pk_mul_f32 v[2:3], v[2:3], v[10:11]
	v_pk_mul_f32 v[4:5], v[4:5], v[12:13]
	v_pk_mul_f32 v[6:7], v[6:7], v[14:15]
	v_cndmask_b32_e64 v1, 1.0, v1, s[34:35]
	v_cndmask_b32_e64 v0, 1.0, v0, s[36:37]
	v_cndmask_b32_e64 v41, 1.0, v3, s[38:39]
	v_cndmask_b32_e64 v40, 1.0, v2, s[40:41]
	v_cndmask_b32_e64 v43, 1.0, v5, s[42:43]
	v_cndmask_b32_e64 v42, 1.0, v4, s[44:45]
	v_cndmask_b32_e64 v45, 1.0, v7, s[46:47]
	v_cndmask_b32_e64 v44, 1.0, v6, s[48:49]
	v_pk_mul_f32 v[0:1], v[0:1], v[40:41]
	v_pk_mul_f32 v[2:3], v[42:43], v[44:45]
	v_cndmask_b32_e64 v76, 0, v47, s[16:17]
	v_pk_mul_f32 v[0:1], v[0:1], v[2:3]
	ds_bpermute_b32 v46, v104, v0
	ds_bpermute_b32 v47, v104, v1
	ds_bpermute_b32 v30, v104, v26
	v_cndmask_b32_e64 v77, 0, v72, s[20:21]
	v_cndmask_b32_e64 v78, 0, v73, s[22:23]
	s_waitcnt lgkmcnt(2)
	v_cndmask_b32_e64 v5, 1.0, v46, s[14:15]
	s_waitcnt lgkmcnt(1)
	v_pk_mul_f32 v[72:73], v[0:1], v[46:47]
	v_mul_f32_e32 v6, v5, v44
	v_mov_b32_e32 v27, v72
	v_mov_b32_e32 v31, v73
	v_cndmask_b32_e64 v2, 0, v10, s[40:41]
	v_mul_f32_e32 v7, v42, v6
	s_waitcnt lgkmcnt(0)
	v_pk_mul_f32 v[0:1], v[26:27], v[30:31]
	ds_bpermute_b32 v28, v104, v24
	v_mul_f32_e32 v42, v2, v7
	v_mul_f32_e32 v2, v1, v30
	v_cndmask_b32_e64 v3, 0, v12, s[44:45]
	v_cndmask_b32_e64 v2, v1, v2, s[14:15]
	v_cndmask_b32_e64 v4, 0, v14, s[48:49]
	v_mul_f32_e32 v111, v3, v6
	v_mul_f32_e32 v3, v105, v2
	v_mul_f32_e32 v44, v5, v4
	v_mul_f32_e32 v4, v29, v3
	v_cndmask_b32_e64 v74, 0, v74, s[26:27]
	v_cndmask_b32_e64 v75, 0, v75, s[30:31]
	v_mul_f32_e32 v5, v25, v4
	v_mov_b32_e32 v25, v0
	v_mov_b32_e32 v29, v1
	v_mul_f32_e32 v2, v75, v2
	v_mul_f32_e32 v4, v74, v4
	s_waitcnt lgkmcnt(0)
; __device__ __forceinline__ void attn_phase(const bf16_t* Q, const bf16_t* KF, const bf16_t* V, bf16_t* VT, bf16_t* O, LAS unsigned char* lds, unsigned* ctr) {
;     ...
;                 { const int ktn = kt > 0 ? kt - 1 : kt;
; #pragma unroll
;                   for (int kd = 0; kd < 4; ++kd) kfn[kd] = *(const bf16x8*)(kfw + (size_t)((ktn * 4 + kd) * 64 + lane) * 8); }
;                 bf16x8 vf[2][2];
; #pragma unroll
;                 for (int db = 0; db < 2; ++db)
; #pragma unroll
;                     for (int ks = 0; ks < 2; ++ks) vf[db][ks] = *(const bf16x8*)(vtb + (size_t)((((kt * 2 + db) * 2 + ks) * 64) + lane) * 8);
	v_pk_mul_f32 v[74:75], v[24:25], v[28:29]
	v_cndmask_b32_e64 v64, 0, v64, s[18:19]
	v_mul_f32_e32 v0, v75, v28
	v_cndmask_b32_e64 v0, v75, v0, s[14:15]
	v_mul_f32_e32 v1, v83, v0
	v_mul_f32_e32 v6, v82, v1
	v_mul_f32_e32 v40, v40, v7
	v_mul_f32_e32 v7, v81, v6
	v_mul_f32_e32 v3, v80, v3
	v_mul_f32_e32 v5, v79, v5
	v_mul_f32_e32 v0, v78, v0
	v_mul_f32_e32 v1, v77, v1
	v_mul_f32_e32 v6, v64, v6
	v_mul_f32_e32 v7, v76, v7
	v_cvt_pk_bf16_f32 v24, v7, v6
	v_cvt_pk_bf16_f32 v25, v1, v0
	v_cvt_pk_bf16_f32 v26, v5, v4
	v_cvt_pk_bf16_f32 v27, v3, v2
	v_cndmask_b32_e64 v106, 0, v9, s[34:35]
	v_cndmask_b32_e64 v107, 0, v11, s[38:39]
	v_cndmask_b32_e64 v108, 0, v13, s[42:43]
	v_cndmask_b32_e64 v109, 0, v15, s[46:47]
	v_cndmask_b32_e64 v110, 0, v8, s[36:37]
	s_waitcnt vmcnt(3)
	v_mfma_f32_32x32x16_bf16 v[0:15], v[20:23], v[24:27], 0
	v_mul_f32_e32 v20, v72, v47
	v_cndmask_b32_e64 v20, v72, v20, s[14:15]
	v_mul_f32_e32 v46, v110, v40
	v_mul_f32_e32 v40, v45, v20
	v_mul_f32_e32 v45, v109, v20
	v_mul_f32_e32 v43, v43, v40
	v_mul_f32_e32 v41, v41, v43
	s_waitcnt vmcnt(1)
	v_mfma_f32_32x32x16_bf16 v[16:31], v[16:19], v[24:27], 0
	v_mul_f32_e32 v47, v108, v40
	v_mul_f32_e32 v40, v107, v43
	v_mul_f32_e32 v41, v106, v41
	v_cvt_pk_bf16_f32 v40, v41, v40
	v_cvt_pk_bf16_f32 v41, v47, v45
	v_cvt_pk_bf16_f32 v42, v46, v42
	v_cvt_pk_bf16_f32 v43, v111, v44
	v_mul_f32_e32 v77, v74, v75
	v_cmp_eq_f32_e32 vcc, 0, v77
	v_mfma_f32_32x32x16_bf16 v[0:15], v[32:35], v[40:43], v[0:15]
	s_cmp_eq_u64 vcc, exec
	s_cselect_b64 s[86:87], -1, 0
	s_cmp_eq_u32 s79, 63
	s_cselect_b64 s[88:89], -1, 0
	s_or_b64 s[86:87], s[88:89], s[86:87]
	s_and_b64 vcc, exec, s[86:87]
	s_waitcnt vmcnt(0)
	v_mfma_f32_32x32x16_bf16 v[16:31], v[36:39], v[40:43], v[16:31]
	s_cbranch_vccnz .LBB0_1743
	s_lshl_b32 s63, s79, 12
	v_subrev_u32_e32 v32, s63, v86
	v_add_u32_e32 v64, 0x3e000, v32
	v_lshl_add_u64 v[32:33], s[82:83], 0, v[64:65]
	s_mov_b64 s[86:87], 0xc00
	s_sub_i32 s63, 62, s79
	s_sub_i32 s72, s79, 62
	s_lshl_b32 s79, s79, 8
	v_lshl_add_u64 v[78:79], v[32:33], 0, s[86:87]
	v_lshl_add_u64 v[80:81], v[32:33], 0, s[74:75]
	v_lshl_add_u64 v[74:75], v[32:33], 0, s[76:77]
	v_subrev_u32_e32 v72, s79, v89
	v_mov_b64_e32 v[82:83], v[64:65]
	v_lshl_add_u64 v[176:177], s[82:83], 0, v[82:83]
	global_load_dwordx4 v[160:163], v[176:177], off
	global_load_dwordx4 v[164:167], v[74:75], off
	global_load_dwordx4 v[168:171], v[80:81], off
	global_load_dwordx4 v[172:175], v[78:79], off
.LBB0_1752:
	s_min_u32 s79, s63, 1
	s_lshl_b32 s79, s79, 8
	v_subrev_u32_e32 v36, s79, v72
	v_add_u32_e32 v38, 0xffffff40, v36
	v_ashrrev_i32_e32 v39, 31, v38
	v_lshlrev_b64 v[82:83], 4, v[38:39]
	v_add_u32_e32 v38, 0xffffff80, v36
	v_ashrrev_i32_e32 v39, 31, v38
	v_lshl_add_u64 v[74:75], v[38:39], 4, s[82:83]
	v_subrev_u32_e32 v38, 64, v36
	v_ashrrev_i32_e32 v39, 31, v38
	v_ashrrev_i32_e32 v37, 31, v36
	v_lshl_add_u64 v[80:81], v[38:39], 4, s[82:83]
	v_lshl_add_u64 v[78:79], v[36:37], 4, s[82:83]
	v_add_u32_e32 v64, 0xffffff40, v72
	v_mov_b32_e32 v73, v65
	v_lshl_add_u64 v[122:123], v[72:73], 4, s[80:81]
	s_waitcnt vmcnt(3)
	v_mfma_f32_32x32x16_bf16 v[32:47], v[160:163], v[48:51], 0
	global_load_dwordx4 v[122:125], v[122:123], off
	s_waitcnt vmcnt(3)
	v_mfma_f32_32x32x16_bf16 v[32:47], v[164:167], v[52:55], v[32:47]
	v_lshl_add_u64 v[106:107], v[64:65], 4, s[80:81]
	v_add_u32_e32 v64, 0xffffff80, v72
	global_load_dwordx4 v[106:109], v[106:107], off
	s_waitcnt vmcnt(3)
	v_mfma_f32_32x32x16_bf16 v[32:47], v[168:171], v[56:59], v[32:47]
	v_lshl_add_u64 v[110:111], v[64:65], 4, s[80:81]
	v_subrev_u32_e32 v64, 64, v72
	v_lshl_add_u64 v[118:119], v[64:65], 4, s[80:81]
	global_load_dwordx4 v[118:121], v[118:119], off
	v_add_u32_e32 v72, 0xffffff00, v72
	global_load_dwordx4 v[110:113], v[110:111], off
	s_waitcnt vmcnt(4)
; __device__ __forceinline__ void attn_phase(const bf16_t* Q, const bf16_t* KF, const bf16_t* V, bf16_t* VT, bf16_t* O, LAS unsigned char* lds, unsigned* ctr) {
;     ...
;                   for (int kd = 0; kd < 4; ++kd) kfn[kd] = *(const bf16x8*)(kfw + (size_t)((ktn * 4 + kd) * 64 + lane) * 8); }
;                 bf16x8 vf[2][2];
; #pragma unroll
;                 for (int db = 0; db < 2; ++db)
; #pragma unroll
;                     for (int ks = 0; ks < 2; ++ks) vf[db][ks] = *(const bf16x8*)(vtb + (size_t)((((kt * 2 + db) * 2 + ks) * 64) + lane) * 8);
;                 float be[16], om[16];
; #pragma unroll
;                 for (int r = 0; r < 16; ++r) { const float e = __builtin_amdgcn_exp2f(-fmaxf(z[r], -80.0f)); be[r] = __builtin_amdgcn_rcpf(1.0f + e); om[r] = e * be[r]; }
;                 if (kt == qb) {
; #pragma unroll
;                     for (int r = 0; r < 16; ++r) { const int sl = 8 * (r >> 2) + 4 * hf + (r & 3); const bool valid = sl < c32; be[r] = valid ? be[r] : 0.f; om[r] = valid ? om[r] : 1.0f; } }
;                 float bp[4], pbp[4];
; #pragma unroll
;                 for (int q = 0; q < 4; ++q) { bp[q] = (om[4 * q] * om[4 * q + 1]) * (om[4 * q + 2] * om[4 * q + 3]); pbp[q] = __shfl_xor(bp[q], 32); }
;                 float after = Pc; float att[16];
; #pragma unroll
;                 for (int q = 3; q >= 0; --q) {
;                     const float off = hf == 0 ? after * pbp[q] : after;
;                     const float e3 = off, e2 = e3 * om[4 * q + 3], e1 = e2 * om[4 * q + 2], e0 = e1 * om[4 * q + 1];
;                     att[4 * q + 3] = be[4 * q + 3] * e3; att[4 * q + 2] = be[4 * q + 2] * e2; att[4 * q + 1] = be[4 * q + 1] * e1; att[4 * q] = be[4 * q] * e0;
;                     after *= bp[q] * pbp[q];
;                 }
;                 Pc = after;
; #pragma unroll
;                 for (int ks = 0; ks < 2; ++ks) {
;                     const bf16x8 pf = __builtin_bit_cast(bf16x8, (u32x4){cvt_pk_bf16(att[8 * ks], att[8 * ks + 1]), cvt_pk_bf16(att[8 * ks + 2], att[8 * ks + 3]), cvt_pk_bf16(att[8 * ks + 4], att[8 * ks + 5]), cvt_pk_bf16(att[8 * ks + 6], att[8 * ks + 7])});
;                     o0 = __builtin_amdgcn_mfma_f32_32x32x16_bf16(vf[0][ks], pf, o0, 0, 0, 0); o1 = __builtin_amdgcn_mfma_f32_32x32x16_bf16(vf[1][ks], pf, o1, 0, 0, 0); }
;                 if (__all(Pc == 0.0f)) break;
	v_mfma_f32_32x32x16_bf16 v[32:47], v[172:175], v[60:63], v[32:47]
	v_lshl_add_u64 v[176:177], s[82:83], 0, v[82:83]
	global_load_dwordx4 v[160:163], v[176:177], off
	global_load_dwordx4 v[164:167], v[74:75], off
	global_load_dwordx4 v[168:171], v[80:81], off
	global_load_dwordx4 v[172:175], v[78:79], off
	s_nop 11
	v_min_f32_e64 v33, -v33, s98
	v_exp_f32_e32 v114, v33
	v_max_f32_e64 v33, -v34, -v34
	v_min_f32_e64 v34, -v35, s98
	v_exp_f32_e32 v115, v34
	v_min_f32_e64 v34, -v36, s98
	v_exp_f32_e32 v34, v34
	v_min_f32_e64 v32, -v32, s98
	v_exp_f32_e32 v32, v32
	v_add_f32_e32 v35, 1.0, v34
	v_rcp_f32_e32 v36, v35
	v_min_f32_e64 v35, -v37, s98
	v_exp_f32_e32 v35, v35
	v_min_f32_e32 v33, 0x42a00000, v33
	v_exp_f32_e32 v33, v33
	v_add_f32_e32 v37, 1.0, v35
	v_rcp_f32_e32 v64, v37
	s_nop 0
	v_mul_f32_e32 v116, v35, v64
	v_min_f32_e64 v35, -v38, s98
	v_exp_f32_e32 v35, v35
	s_nop 0
	v_add_f32_e32 v37, 1.0, v35
	v_rcp_f32_e32 v73, v37
	s_nop 0
	v_mul_f32_e32 v76, v35, v73
	v_min_f32_e64 v35, -v39, s98
	v_exp_f32_e32 v38, v35
	s_nop 0
	v_add_f32_e32 v35, 1.0, v38
	v_rcp_f32_e32 v126, v35
	v_min_f32_e64 v35, -v40, s98
	v_exp_f32_e32 v40, v35
	v_min_f32_e64 v35, -v41, s98
	v_exp_f32_e32 v41, v35
	v_add_f32_e32 v35, 1.0, v40
	v_rcp_f32_e32 v128, v35
	v_add_f32_e32 v35, 1.0, v41
	v_rcp_f32_e32 v129, v35
	v_min_f32_e64 v35, -v42, s98
	v_exp_f32_e32 v42, v35
	v_min_f32_e64 v35, -v43, s98
	v_exp_f32_e32 v43, v35
	v_add_f32_e32 v35, 1.0, v42
	v_rcp_f32_e32 v130, v35
	v_pk_mul_f32 v[40:41], v[40:41], v[128:129]
	v_add_f32_e32 v35, 1.0, v43
	v_rcp_f32_e32 v131, v35
	v_min_f32_e64 v35, -v44, s98
	v_exp_f32_e32 v44, v35
	v_min_f32_e64 v35, -v45, s98
	v_exp_f32_e32 v132, v35
	v_min_f32_e64 v35, -v46, s98
	v_exp_f32_e32 v45, v35
	v_min_f32_e64 v35, -v47, s98
	v_exp_f32_e32 v133, v35
	v_add_f32_e32 v35, 1.0, v32
	v_rcp_f32_e32 v46, v35
	v_add_f32_e32 v35, 1.0, v114
	v_rcp_f32_e32 v134, v35
	v_add_f32_e32 v35, 1.0, v33
	v_rcp_f32_e32 v47, v35
	v_add_f32_e32 v35, 1.0, v115
	v_rcp_f32_e32 v135, v35
	v_pk_mul_f32 v[42:43], v[42:43], v[130:131]
	v_pk_mul_f32 v[32:33], v[32:33], v[46:47]
	v_pk_mul_f32 v[138:139], v[40:41], v[40:41] op_sel_hi:[0,1]
	v_pk_mul_f32 v[114:115], v[114:115], v[134:135]
	v_pk_mul_f32 v[140:141], v[42:43], v[42:43] op_sel_hi:[0,1]
	v_pk_mul_f32 v[136:137], v[32:33], v[114:115]
	v_add_f32_e32 v32, 1.0, v44
	v_rcp_f32_e32 v142, v32
	v_add_f32_e32 v32, 1.0, v132
	v_rcp_f32_e32 v144, v32
	v_add_f32_e32 v32, 1.0, v45
	v_rcp_f32_e32 v143, v32
	v_add_f32_e32 v32, 1.0, v133
	v_rcp_f32_e32 v145, v32
	v_pk_mul_f32 v[44:45], v[44:45], v[142:143]
	v_pk_mul_f32 v[132:133], v[132:133], v[144:145]
	s_nop 0
	v_pk_mul_f32 v[146:147], v[44:45], v[132:133]
	s_nop 0
	v_pk_mul_f32 v[146:147], v[146:147], v[146:147] op_sel:[0,1] op_sel_hi:[1,0]
	v_mov_b32_e32 v178, v146
	v_mov_b32_e32 v179, v146
	s_nop 1
	v_permlane32_swap_b32_e32 v178, v179
	v_cndmask_b32_e64 v127, v178, v179, s[14:15]
	v_mul_f32_e32 v32, v77, v127
	v_cndmask_b32_e64 v32, v77, v32, s[14:15]
	v_mul_f32_e32 v35, v32, v133
	v_mul_f32_e32 v37, v45, v35
	v_mul_f32_e32 v39, v132, v37
	v_mul_f32_e32 v105, v143, v35
	v_mul_f32_e32 v132, v144, v37
	v_mov_b32_e32 v35, v139
	v_mov_b32_e32 v37, v141
	v_pk_mul_f32 v[34:35], v[34:35], v[36:37]
	v_mov_b32_e32 v178, v35
	v_mov_b32_e32 v179, v35
	s_nop 1
	v_permlane32_swap_b32_e32 v178, v179
	v_cndmask_b32_e64 v117, v178, v179, s[14:15]
	v_mul_f32_e32 v133, v142, v39
	v_mov_b32_e32 v39, v146
	v_pk_mul_f32 v[38:39], v[38:39], v[126:127]
	v_mul_f32_e32 v40, v32, v145
	v_pk_mul_f32 v[44:45], v[76:77], v[38:39]
	v_pk_mul_f32 v[34:35], v[34:35], v[116:117]
	v_mul_f32_e32 v32, v45, v117
	v_pk_mul_f32 v[34:35], v[34:35], v[44:45]
	v_mov_b32_e32 v178, v34
	v_mov_b32_e32 v179, v34
	s_nop 1
	v_permlane32_swap_b32_e32 v178, v179
	v_cndmask_b32_e64 v37, v178, v179, s[14:15]
	v_cndmask_b32_e64 v32, v45, v32, s[14:15]
	v_mul_f32_e32 v39, v43, v32
	v_mul_f32_e32 v43, v131, v32
	v_mul_f32_e32 v42, v42, v39
	v_mul_f32_e32 v32, v35, v37
	v_cndmask_b32_e64 v32, v35, v32, s[14:15]
	v_mul_f32_e32 v38, v38, v32
	v_mul_f32_e32 v44, v130, v39
	v_mul_f32_e32 v39, v76, v38
	v_mul_f32_e32 v45, v116, v39
	v_mul_f32_e32 v73, v73, v38
	v_mul_f32_e32 v64, v64, v39
	v_mul_f32_e32 v45, v36, v45
	v_mov_b32_e32 v38, v136
	v_mov_b32_e32 v39, v34
	v_mov_b32_e32 v36, v137
	v_pk_mul_f32 v[36:37], v[38:39], v[36:37]
	v_mov_b32_e32 v178, v36
	v_mov_b32_e32 v179, v36
	s_nop 1
	v_permlane32_swap_b32_e32 v178, v179
	v_cndmask_b32_e64 v34, v178, v179, s[14:15]
	v_mul_f32_e32 v76, v126, v32
	v_mul_f32_e32 v41, v41, v42
	v_mul_f32_e32 v42, v129, v42
	v_mul_f32_e32 v41, v128, v41
	v_pk_mul_f32 v[36:37], v[36:37], v[34:35]
	s_nop 0
	v_mul_f32_e32 v32, v37, v34
	v_cndmask_b32_e64 v32, v37, v32, s[14:15]
	v_mul_f32_e32 v34, v115, v32
	v_mul_f32_e32 v33, v33, v34
	v_mul_f32_e32 v35, v114, v33
	v_mul_f32_e32 v38, v135, v32
	v_mul_f32_e32 v34, v47, v34
	v_mul_f32_e32 v32, v134, v33
	v_mul_f32_e32 v33, v46, v35
	v_cvt_pk_bf16_f32 v32, v33, v32
	v_cvt_pk_bf16_f32 v33, v34, v38
	v_cvt_pk_bf16_f32 v34, v45, v64
	v_cvt_pk_bf16_f32 v35, v73, v76
	v_mul_f32_e32 v77, v36, v37
	v_cmp_eq_f32_e32 vcc, 0, v77
	s_waitcnt vmcnt(6)
	v_mfma_f32_32x32x16_bf16 v[0:15], v[106:109], v[32:35], v[0:15]
	s_cmp_lg_u64 vcc, exec
	s_cselect_b64 s[86:87], -1, 0
	s_add_i32 s63, s63, -1
	s_cmp_lg_u32 s72, 0
	s_cselect_b64 s[88:89], -1, 0
	s_and_b64 s[86:87], s[88:89], s[86:87]
	s_add_i32 s72, s72, 1
	s_waitcnt vmcnt(5)
	v_mfma_f32_32x32x16_bf16 v[16:31], v[118:121], v[32:35], v[16:31]
	v_cvt_pk_bf16_f32 v32, v41, v42
	v_cvt_pk_bf16_f32 v33, v44, v43
	v_cvt_pk_bf16_f32 v34, v133, v132
	v_cvt_pk_bf16_f32 v35, v105, v40
	s_and_b64 vcc, exec, s[86:87]
	s_waitcnt vmcnt(4)
	v_mfma_f32_32x32x16_bf16 v[0:15], v[110:113], v[32:35], v[0:15]
	v_mfma_f32_32x32x16_bf16 v[16:31], v[122:125], v[32:35], v[16:31]
	s_cbranch_vccnz .LBB0_1752
	s_waitcnt vmcnt(0)
	s_branch .LBB0_1743
